# scanner: step-0 operand reads issued at the top of the first slot after the chunk barrier
# baseline (speedup 1.0000x reference)
.LBB0_787:
	s_and_saveexec_b64 s[0:1], s[8:9]
	s_xor_b64 s[36:37], exec, s[0:1]
	s_cbranch_execz .LBB0_791
	s_and_saveexec_b64 s[44:45], s[26:27]
	s_cbranch_execz .LBB0_790
	s_and_b32 s0, s54, 1
	s_mul_i32 s1, s0, 0xc000
	s_lshl_b32 s4, s30, 2
	v_add_u32_e32 v10, s1, v97
	s_add_i32 s1, s1, s4
	v_lshl_add_u32 v11, v95, 2, s1
	v_lshl_add_u32 v12, s0, 14, v102
	ds_read_b128 v[40:43], v10 offset:768
	ds_read_b128 v[36:39], v10 offset:512
	ds_read2st64_b32 v[0:1], v11 offset0:5 offset1:11
	ds_read_b128 v[28:31], v10 offset:0
	ds_read_b128 v[44:47], v10 offset:1024
	ds_read_b128 v[32:35], v10 offset:256
	v_pk_fma_f32 v[4:5], v[60:61], v[64:65], v[56:57] op_sel_hi:[0,1,1]
	v_pk_fma_f32 v[6:7], v[60:61], v[66:67], v[58:59] op_sel_hi:[0,1,1]
	v_pk_mul_f32 v[80:81], v[4:5], v[80:81]
	v_pk_fma_f32 v[80:81], v[6:7], v[82:83], v[80:81]
	v_add_f32_e32 v80, v80, v81
	v_pk_mul_f32 v[76:77], v[76:77], v[2:3] op_sel_hi:[1,0]
	v_pk_mul_f32 v[78:79], v[78:79], v[2:3] op_sel_hi:[1,0]
	v_add_f32_dpp v80, v80, v80 quad_perm:[1,0,3,2] row_mask:0xf bank_mask:0xf bound_ctrl:1
	v_pk_fma_f32 v[76:77], v[4:5], v[68:69], v[76:77]
	v_pk_fma_f32 v[78:79], v[6:7], v[70:71], v[78:79]
	v_add_f32_dpp v80, v80, v80 quad_perm:[2,3,0,1] row_mask:0xf bank_mask:0xf bound_ctrl:1
	v_pk_mul_f32 v[52:53], v[52:53], v[4:5]
	v_pk_fma_f32 v[52:53], v[6:7], v[54:55], v[52:53]
	v_add_f32_dpp v80, v80, v80 row_half_mirror row_mask:0xf bank_mask:0xf bound_ctrl:1
	v_add_f32_e32 v9, v52, v53
	ds_read_b128 v[56:59], v10 offset:2048
	ds_read_b128 v[60:63], v10 offset:2304
	ds_read_b128 v[48:51], v10 offset:1536
	ds_read_b128 v[64:67], v10 offset:2560
	ds_read_b128 v[52:55], v10 offset:1792
	v_add_f32_dpp v80, v80, v80 row_mirror row_mask:0xf bank_mask:0xf bound_ctrl:1
	v_pk_fma_f32 v[4:5], v[80:81], v[84:85], v[76:77] op_sel_hi:[0,1,1]
	v_pk_fma_f32 v[6:7], v[80:81], v[86:87], v[78:79] op_sel_hi:[0,1,1]
	v_pk_mul_f32 v[116:117], v[4:5], v[116:117]
	v_pk_fma_f32 v[116:117], v[6:7], v[118:119], v[116:117]
	v_add_f32_e32 v116, v116, v117
	v_pk_mul_f32 v[112:113], v[112:113], v[2:3] op_sel:[0,1] op_sel_hi:[1,1]
	v_pk_mul_f32 v[114:115], v[114:115], v[2:3] op_sel:[0,1] op_sel_hi:[1,1]
	v_add_f32_dpp v116, v116, v116 quad_perm:[1,0,3,2] row_mask:0xf bank_mask:0xf bound_ctrl:1
	v_pk_fma_f32 v[112:113], v[4:5], v[104:105], v[112:113]
	v_pk_fma_f32 v[114:115], v[6:7], v[106:107], v[114:115]
	v_add_f32_dpp v116, v116, v116 quad_perm:[2,3,0,1] row_mask:0xf bank_mask:0xf bound_ctrl:1
	v_pk_mul_f32 v[72:73], v[72:73], v[4:5]
	v_pk_fma_f32 v[72:73], v[6:7], v[74:75], v[72:73]
	v_add_f32_dpp v116, v116, v116 row_half_mirror row_mask:0xf bank_mask:0xf bound_ctrl:1
	v_add_f32_e32 v8, v72, v73
	ds_read_b128 v[76:79], v10 offset:3584
	ds_read2st64_b32 v[2:3], v11 offset0:17 offset1:23
	ds_read_b128 v[80:83], v10 offset:3840
	ds_read_b128 v[68:71], v10 offset:3072
	ds_read_b128 v[84:87], v10 offset:4096
	ds_read_b128 v[72:75], v10 offset:3328
	ds_write2st64_b32 v12, v9, v8 offset0:0 offset1:2
	v_add_f32_dpp v116, v116, v116 row_mirror row_mask:0xf bank_mask:0xf bound_ctrl:1
	v_pk_fma_f32 v[4:5], v[116:117], v[120:121], v[112:113] op_sel_hi:[0,1,1]
	v_pk_fma_f32 v[6:7], v[116:117], v[122:123], v[114:115] op_sel_hi:[0,1,1]
	s_waitcnt lgkmcnt(12)
	v_pk_mul_f32 v[40:41], v[4:5], v[40:41]
	v_pk_fma_f32 v[40:41], v[6:7], v[42:43], v[40:41]
	v_add_f32_e32 v40, v40, v41
	v_pk_mul_f32 v[36:37], v[36:37], v[0:1] op_sel_hi:[1,0]
	v_pk_mul_f32 v[38:39], v[38:39], v[0:1] op_sel_hi:[1,0]
	v_add_f32_dpp v40, v40, v40 quad_perm:[1,0,3,2] row_mask:0xf bank_mask:0xf bound_ctrl:1
	v_pk_fma_f32 v[36:37], v[4:5], v[28:29], v[36:37]
	v_pk_fma_f32 v[38:39], v[6:7], v[30:31], v[38:39]
	v_add_f32_dpp v40, v40, v40 quad_perm:[2,3,0,1] row_mask:0xf bank_mask:0xf bound_ctrl:1
	v_pk_mul_f32 v[108:109], v[108:109], v[4:5]
	v_pk_fma_f32 v[108:109], v[6:7], v[110:111], v[108:109]
	v_add_f32_dpp v40, v40, v40 row_half_mirror row_mask:0xf bank_mask:0xf bound_ctrl:1
	v_add_f32_e32 v9, v108, v109
	ds_read_b128 v[112:115], v10 offset:5120
	ds_read_b128 v[116:119], v10 offset:5376
	ds_read_b128 v[104:107], v10 offset:4608
	ds_read_b128 v[120:123], v10 offset:5632
	ds_read_b128 v[108:111], v10 offset:4864
	v_add_f32_dpp v40, v40, v40 row_mirror row_mask:0xf bank_mask:0xf bound_ctrl:1
	v_pk_fma_f32 v[4:5], v[40:41], v[44:45], v[36:37] op_sel_hi:[0,1,1]
	v_pk_fma_f32 v[6:7], v[40:41], v[46:47], v[38:39] op_sel_hi:[0,1,1]
	s_waitcnt lgkmcnt(12)
	v_pk_mul_f32 v[60:61], v[4:5], v[60:61]
	v_pk_fma_f32 v[60:61], v[6:7], v[62:63], v[60:61]
	v_add_f32_e32 v60, v60, v61
	v_pk_mul_f32 v[56:57], v[56:57], v[0:1] op_sel:[0,1] op_sel_hi:[1,1]
	v_pk_mul_f32 v[58:59], v[58:59], v[0:1] op_sel:[0,1] op_sel_hi:[1,1]
	v_add_f32_dpp v60, v60, v60 quad_perm:[1,0,3,2] row_mask:0xf bank_mask:0xf bound_ctrl:1
	v_pk_fma_f32 v[56:57], v[4:5], v[48:49], v[56:57]
	v_pk_fma_f32 v[58:59], v[6:7], v[50:51], v[58:59]
	v_add_f32_dpp v60, v60, v60 quad_perm:[2,3,0,1] row_mask:0xf bank_mask:0xf bound_ctrl:1
	v_pk_mul_f32 v[32:33], v[32:33], v[4:5]
	v_pk_fma_f32 v[32:33], v[6:7], v[34:35], v[32:33]
	v_add_f32_dpp v60, v60, v60 row_half_mirror row_mask:0xf bank_mask:0xf bound_ctrl:1
	v_add_f32_e32 v8, v32, v33
	ds_read_b128 v[36:39], v10 offset:6656
	ds_read2st64_b32 v[0:1], v11 offset0:29 offset1:35
	ds_read_b128 v[40:43], v10 offset:6912
	ds_read_b128 v[28:31], v10 offset:6144
	ds_read_b128 v[44:47], v10 offset:7168
	ds_read_b128 v[32:35], v10 offset:6400
	ds_write2st64_b32 v12, v9, v8 offset0:4 offset1:6
	v_add_f32_dpp v60, v60, v60 row_mirror row_mask:0xf bank_mask:0xf bound_ctrl:1
	v_pk_fma_f32 v[4:5], v[60:61], v[64:65], v[56:57] op_sel_hi:[0,1,1]
	v_pk_fma_f32 v[6:7], v[60:61], v[66:67], v[58:59] op_sel_hi:[0,1,1]
	s_waitcnt lgkmcnt(13)
	v_pk_mul_f32 v[80:81], v[4:5], v[80:81]
	v_pk_fma_f32 v[80:81], v[6:7], v[82:83], v[80:81]
	v_add_f32_e32 v80, v80, v81
	v_pk_mul_f32 v[76:77], v[76:77], v[2:3] op_sel_hi:[1,0]
	v_pk_mul_f32 v[78:79], v[78:79], v[2:3] op_sel_hi:[1,0]
	v_add_f32_dpp v80, v80, v80 quad_perm:[1,0,3,2] row_mask:0xf bank_mask:0xf bound_ctrl:1
	v_pk_fma_f32 v[76:77], v[4:5], v[68:69], v[76:77]
	v_pk_fma_f32 v[78:79], v[6:7], v[70:71], v[78:79]
	v_add_f32_dpp v80, v80, v80 quad_perm:[2,3,0,1] row_mask:0xf bank_mask:0xf bound_ctrl:1
	v_pk_mul_f32 v[52:53], v[52:53], v[4:5]
	v_pk_fma_f32 v[52:53], v[6:7], v[54:55], v[52:53]
	v_add_f32_dpp v80, v80, v80 row_half_mirror row_mask:0xf bank_mask:0xf bound_ctrl:1
	v_add_f32_e32 v9, v52, v53
	ds_read_b128 v[56:59], v10 offset:8192
	ds_read_b128 v[60:63], v10 offset:8448
	ds_read_b128 v[48:51], v10 offset:7680
	ds_read_b128 v[64:67], v10 offset:8704
	ds_read_b128 v[52:55], v10 offset:7936
	v_add_f32_dpp v80, v80, v80 row_mirror row_mask:0xf bank_mask:0xf bound_ctrl:1
	v_pk_fma_f32 v[4:5], v[80:81], v[84:85], v[76:77] op_sel_hi:[0,1,1]
	v_pk_fma_f32 v[6:7], v[80:81], v[86:87], v[78:79] op_sel_hi:[0,1,1]
	s_waitcnt lgkmcnt(12)
	v_pk_mul_f32 v[116:117], v[4:5], v[116:117]
	v_pk_fma_f32 v[116:117], v[6:7], v[118:119], v[116:117]
	v_add_f32_e32 v116, v116, v117
	v_pk_mul_f32 v[112:113], v[112:113], v[2:3] op_sel:[0,1] op_sel_hi:[1,1]
	v_pk_mul_f32 v[114:115], v[114:115], v[2:3] op_sel:[0,1] op_sel_hi:[1,1]
	v_add_f32_dpp v116, v116, v116 quad_perm:[1,0,3,2] row_mask:0xf bank_mask:0xf bound_ctrl:1
	v_pk_fma_f32 v[112:113], v[4:5], v[104:105], v[112:113]
	v_pk_fma_f32 v[114:115], v[6:7], v[106:107], v[114:115]
	v_add_f32_dpp v116, v116, v116 quad_perm:[2,3,0,1] row_mask:0xf bank_mask:0xf bound_ctrl:1
	v_pk_mul_f32 v[72:73], v[72:73], v[4:5]
	v_pk_fma_f32 v[72:73], v[6:7], v[74:75], v[72:73]
	v_add_f32_dpp v116, v116, v116 row_half_mirror row_mask:0xf bank_mask:0xf bound_ctrl:1
	v_add_f32_e32 v8, v72, v73
	ds_read_b128 v[76:79], v10 offset:9728
	ds_read2st64_b32 v[2:3], v11 offset0:41 offset1:47
	ds_read_b128 v[80:83], v10 offset:9984
	ds_read_b128 v[68:71], v10 offset:9216
	ds_read_b128 v[84:87], v10 offset:10240
	ds_read_b128 v[72:75], v10 offset:9472
	ds_write2st64_b32 v12, v9, v8 offset0:8 offset1:10
	v_add_f32_dpp v116, v116, v116 row_mirror row_mask:0xf bank_mask:0xf bound_ctrl:1
	v_pk_fma_f32 v[4:5], v[116:117], v[120:121], v[112:113] op_sel_hi:[0,1,1]
	v_pk_fma_f32 v[6:7], v[116:117], v[122:123], v[114:115] op_sel_hi:[0,1,1]
	s_waitcnt lgkmcnt(13)
	v_pk_mul_f32 v[40:41], v[4:5], v[40:41]
	v_pk_fma_f32 v[40:41], v[6:7], v[42:43], v[40:41]
	v_add_f32_e32 v40, v40, v41
	v_pk_mul_f32 v[36:37], v[36:37], v[0:1] op_sel_hi:[1,0]
	v_pk_mul_f32 v[38:39], v[38:39], v[0:1] op_sel_hi:[1,0]
	v_add_f32_dpp v40, v40, v40 quad_perm:[1,0,3,2] row_mask:0xf bank_mask:0xf bound_ctrl:1
	v_pk_fma_f32 v[36:37], v[4:5], v[28:29], v[36:37]
	v_pk_fma_f32 v[38:39], v[6:7], v[30:31], v[38:39]
	v_add_f32_dpp v40, v40, v40 quad_perm:[2,3,0,1] row_mask:0xf bank_mask:0xf bound_ctrl:1
	v_pk_mul_f32 v[108:109], v[108:109], v[4:5]
	v_pk_fma_f32 v[108:109], v[6:7], v[110:111], v[108:109]
	v_add_f32_dpp v40, v40, v40 row_half_mirror row_mask:0xf bank_mask:0xf bound_ctrl:1
	v_add_f32_e32 v9, v108, v109
	ds_read_b128 v[112:115], v10 offset:11264
	ds_read_b128 v[116:119], v10 offset:11520
	ds_read_b128 v[104:107], v10 offset:10752
	ds_read_b128 v[120:123], v10 offset:11776
	ds_read_b128 v[108:111], v10 offset:11008
	v_add_f32_dpp v40, v40, v40 row_mirror row_mask:0xf bank_mask:0xf bound_ctrl:1
	v_pk_fma_f32 v[4:5], v[40:41], v[44:45], v[36:37] op_sel_hi:[0,1,1]
	v_pk_fma_f32 v[6:7], v[40:41], v[46:47], v[38:39] op_sel_hi:[0,1,1]
	s_waitcnt lgkmcnt(12)
	v_pk_mul_f32 v[60:61], v[4:5], v[60:61]
	v_pk_fma_f32 v[60:61], v[6:7], v[62:63], v[60:61]
	v_add_f32_e32 v60, v60, v61
	v_pk_mul_f32 v[56:57], v[56:57], v[0:1] op_sel:[0,1] op_sel_hi:[1,1]
	v_pk_mul_f32 v[58:59], v[58:59], v[0:1] op_sel:[0,1] op_sel_hi:[1,1]
	v_add_f32_dpp v60, v60, v60 quad_perm:[1,0,3,2] row_mask:0xf bank_mask:0xf bound_ctrl:1
	v_pk_fma_f32 v[56:57], v[4:5], v[48:49], v[56:57]
	v_pk_fma_f32 v[58:59], v[6:7], v[50:51], v[58:59]
	v_add_f32_dpp v60, v60, v60 quad_perm:[2,3,0,1] row_mask:0xf bank_mask:0xf bound_ctrl:1
	v_pk_mul_f32 v[32:33], v[32:33], v[4:5]
	v_pk_fma_f32 v[32:33], v[6:7], v[34:35], v[32:33]
	v_add_f32_dpp v60, v60, v60 row_half_mirror row_mask:0xf bank_mask:0xf bound_ctrl:1
	v_add_f32_e32 v8, v32, v33
	ds_read_b128 v[36:39], v10 offset:12800
	ds_read2st64_b32 v[0:1], v11 offset0:53 offset1:59
	ds_read_b128 v[40:43], v10 offset:13056
	ds_read_b128 v[28:31], v10 offset:12288
	ds_read_b128 v[44:47], v10 offset:13312
	ds_read_b128 v[32:35], v10 offset:12544
	ds_write2st64_b32 v12, v9, v8 offset0:12 offset1:14
	v_add_f32_dpp v60, v60, v60 row_mirror row_mask:0xf bank_mask:0xf bound_ctrl:1
	v_pk_fma_f32 v[4:5], v[60:61], v[64:65], v[56:57] op_sel_hi:[0,1,1]
	v_pk_fma_f32 v[6:7], v[60:61], v[66:67], v[58:59] op_sel_hi:[0,1,1]
	s_waitcnt lgkmcnt(13)
	v_pk_mul_f32 v[80:81], v[4:5], v[80:81]
	v_pk_fma_f32 v[80:81], v[6:7], v[82:83], v[80:81]
	v_add_f32_e32 v80, v80, v81
	v_pk_mul_f32 v[76:77], v[76:77], v[2:3] op_sel_hi:[1,0]
	v_pk_mul_f32 v[78:79], v[78:79], v[2:3] op_sel_hi:[1,0]
	v_add_f32_dpp v80, v80, v80 quad_perm:[1,0,3,2] row_mask:0xf bank_mask:0xf bound_ctrl:1
	v_pk_fma_f32 v[76:77], v[4:5], v[68:69], v[76:77]
	v_pk_fma_f32 v[78:79], v[6:7], v[70:71], v[78:79]
	v_add_f32_dpp v80, v80, v80 quad_perm:[2,3,0,1] row_mask:0xf bank_mask:0xf bound_ctrl:1
	v_pk_mul_f32 v[52:53], v[52:53], v[4:5]
	v_pk_fma_f32 v[52:53], v[6:7], v[54:55], v[52:53]
	v_add_f32_dpp v80, v80, v80 row_half_mirror row_mask:0xf bank_mask:0xf bound_ctrl:1
	v_add_f32_e32 v9, v52, v53
	ds_read_b128 v[56:59], v10 offset:14336
	ds_read_b128 v[60:63], v10 offset:14592
	ds_read_b128 v[48:51], v10 offset:13824
	ds_read_b128 v[64:67], v10 offset:14848
	ds_read_b128 v[52:55], v10 offset:14080
	v_add_f32_dpp v80, v80, v80 row_mirror row_mask:0xf bank_mask:0xf bound_ctrl:1
	v_pk_fma_f32 v[4:5], v[80:81], v[84:85], v[76:77] op_sel_hi:[0,1,1]
	v_pk_fma_f32 v[6:7], v[80:81], v[86:87], v[78:79] op_sel_hi:[0,1,1]
	s_waitcnt lgkmcnt(12)
	v_pk_mul_f32 v[116:117], v[4:5], v[116:117]
	v_pk_fma_f32 v[116:117], v[6:7], v[118:119], v[116:117]
	v_add_f32_e32 v116, v116, v117
	v_pk_mul_f32 v[112:113], v[112:113], v[2:3] op_sel:[0,1] op_sel_hi:[1,1]
	v_pk_mul_f32 v[114:115], v[114:115], v[2:3] op_sel:[0,1] op_sel_hi:[1,1]
	v_add_f32_dpp v116, v116, v116 quad_perm:[1,0,3,2] row_mask:0xf bank_mask:0xf bound_ctrl:1
	v_pk_fma_f32 v[112:113], v[4:5], v[104:105], v[112:113]
	v_pk_fma_f32 v[114:115], v[6:7], v[106:107], v[114:115]
	v_add_f32_dpp v116, v116, v116 quad_perm:[2,3,0,1] row_mask:0xf bank_mask:0xf bound_ctrl:1
	v_pk_mul_f32 v[72:73], v[72:73], v[4:5]
	v_pk_fma_f32 v[72:73], v[6:7], v[74:75], v[72:73]
	v_add_f32_dpp v116, v116, v116 row_half_mirror row_mask:0xf bank_mask:0xf bound_ctrl:1
	v_add_f32_e32 v8, v72, v73
	ds_read_b128 v[76:79], v10 offset:15872
	ds_read2st64_b32 v[2:3], v11 offset0:65 offset1:71
	ds_read_b128 v[80:83], v10 offset:16128
	ds_read_b128 v[68:71], v10 offset:15360
	ds_read_b128 v[84:87], v10 offset:16384
	ds_read_b128 v[72:75], v10 offset:15616
	ds_write2st64_b32 v12, v9, v8 offset0:16 offset1:18
	v_add_f32_dpp v116, v116, v116 row_mirror row_mask:0xf bank_mask:0xf bound_ctrl:1
	v_pk_fma_f32 v[4:5], v[116:117], v[120:121], v[112:113] op_sel_hi:[0,1,1]
	v_pk_fma_f32 v[6:7], v[116:117], v[122:123], v[114:115] op_sel_hi:[0,1,1]
	s_waitcnt lgkmcnt(13)
	v_pk_mul_f32 v[40:41], v[4:5], v[40:41]
	v_pk_fma_f32 v[40:41], v[6:7], v[42:43], v[40:41]
	v_add_f32_e32 v40, v40, v41
	v_pk_mul_f32 v[36:37], v[36:37], v[0:1] op_sel_hi:[1,0]
	v_pk_mul_f32 v[38:39], v[38:39], v[0:1] op_sel_hi:[1,0]
	v_add_f32_dpp v40, v40, v40 quad_perm:[1,0,3,2] row_mask:0xf bank_mask:0xf bound_ctrl:1
	v_pk_fma_f32 v[36:37], v[4:5], v[28:29], v[36:37]
	v_pk_fma_f32 v[38:39], v[6:7], v[30:31], v[38:39]
	v_add_f32_dpp v40, v40, v40 quad_perm:[2,3,0,1] row_mask:0xf bank_mask:0xf bound_ctrl:1
	v_pk_mul_f32 v[108:109], v[108:109], v[4:5]
	v_pk_fma_f32 v[108:109], v[6:7], v[110:111], v[108:109]
	v_add_f32_dpp v40, v40, v40 row_half_mirror row_mask:0xf bank_mask:0xf bound_ctrl:1
	v_add_f32_e32 v9, v108, v109
	ds_read_b128 v[112:115], v10 offset:17408
	ds_read_b128 v[116:119], v10 offset:17664
	ds_read_b128 v[104:107], v10 offset:16896
	ds_read_b128 v[120:123], v10 offset:17920
	ds_read_b128 v[108:111], v10 offset:17152
	v_add_f32_dpp v40, v40, v40 row_mirror row_mask:0xf bank_mask:0xf bound_ctrl:1
	v_pk_fma_f32 v[4:5], v[40:41], v[44:45], v[36:37] op_sel_hi:[0,1,1]
	v_pk_fma_f32 v[6:7], v[40:41], v[46:47], v[38:39] op_sel_hi:[0,1,1]
	s_waitcnt lgkmcnt(12)
	v_pk_mul_f32 v[60:61], v[4:5], v[60:61]
	v_pk_fma_f32 v[60:61], v[6:7], v[62:63], v[60:61]
	v_add_f32_e32 v60, v60, v61
	v_pk_mul_f32 v[56:57], v[56:57], v[0:1] op_sel:[0,1] op_sel_hi:[1,1]
	v_pk_mul_f32 v[58:59], v[58:59], v[0:1] op_sel:[0,1] op_sel_hi:[1,1]
	v_add_f32_dpp v60, v60, v60 quad_perm:[1,0,3,2] row_mask:0xf bank_mask:0xf bound_ctrl:1
	v_pk_fma_f32 v[56:57], v[4:5], v[48:49], v[56:57]
	v_pk_fma_f32 v[58:59], v[6:7], v[50:51], v[58:59]
	v_add_f32_dpp v60, v60, v60 quad_perm:[2,3,0,1] row_mask:0xf bank_mask:0xf bound_ctrl:1
	v_pk_mul_f32 v[32:33], v[32:33], v[4:5]
	v_pk_fma_f32 v[32:33], v[6:7], v[34:35], v[32:33]
	v_add_f32_dpp v60, v60, v60 row_half_mirror row_mask:0xf bank_mask:0xf bound_ctrl:1
	v_add_f32_e32 v8, v32, v33
	ds_read_b128 v[36:39], v10 offset:18944
	ds_read2st64_b32 v[0:1], v11 offset0:77 offset1:83
	ds_read_b128 v[40:43], v10 offset:19200
	ds_read_b128 v[28:31], v10 offset:18432
	ds_read_b128 v[44:47], v10 offset:19456
	ds_read_b128 v[32:35], v10 offset:18688
	ds_write2st64_b32 v12, v9, v8 offset0:20 offset1:22
	v_add_f32_dpp v60, v60, v60 row_mirror row_mask:0xf bank_mask:0xf bound_ctrl:1
	v_pk_fma_f32 v[4:5], v[60:61], v[64:65], v[56:57] op_sel_hi:[0,1,1]
	v_pk_fma_f32 v[6:7], v[60:61], v[66:67], v[58:59] op_sel_hi:[0,1,1]
	s_waitcnt lgkmcnt(13)
	v_pk_mul_f32 v[80:81], v[4:5], v[80:81]
	v_pk_fma_f32 v[80:81], v[6:7], v[82:83], v[80:81]
	v_add_f32_e32 v80, v80, v81
	v_pk_mul_f32 v[76:77], v[76:77], v[2:3] op_sel_hi:[1,0]
	v_pk_mul_f32 v[78:79], v[78:79], v[2:3] op_sel_hi:[1,0]
	v_add_f32_dpp v80, v80, v80 quad_perm:[1,0,3,2] row_mask:0xf bank_mask:0xf bound_ctrl:1
	v_pk_fma_f32 v[76:77], v[4:5], v[68:69], v[76:77]
	v_pk_fma_f32 v[78:79], v[6:7], v[70:71], v[78:79]
	v_add_f32_dpp v80, v80, v80 quad_perm:[2,3,0,1] row_mask:0xf bank_mask:0xf bound_ctrl:1
	v_pk_mul_f32 v[52:53], v[52:53], v[4:5]
	v_pk_fma_f32 v[52:53], v[6:7], v[54:55], v[52:53]
	v_add_f32_dpp v80, v80, v80 row_half_mirror row_mask:0xf bank_mask:0xf bound_ctrl:1
	v_add_f32_e32 v9, v52, v53
	ds_read_b128 v[56:59], v10 offset:20480
	ds_read_b128 v[60:63], v10 offset:20736
	ds_read_b128 v[48:51], v10 offset:19968
	ds_read_b128 v[64:67], v10 offset:20992
	ds_read_b128 v[52:55], v10 offset:20224
	v_add_f32_dpp v80, v80, v80 row_mirror row_mask:0xf bank_mask:0xf bound_ctrl:1
	v_pk_fma_f32 v[4:5], v[80:81], v[84:85], v[76:77] op_sel_hi:[0,1,1]
	v_pk_fma_f32 v[6:7], v[80:81], v[86:87], v[78:79] op_sel_hi:[0,1,1]
	s_waitcnt lgkmcnt(12)
	v_pk_mul_f32 v[116:117], v[4:5], v[116:117]
	v_pk_fma_f32 v[116:117], v[6:7], v[118:119], v[116:117]
	v_add_f32_e32 v116, v116, v117
	v_pk_mul_f32 v[112:113], v[112:113], v[2:3] op_sel:[0,1] op_sel_hi:[1,1]
	v_pk_mul_f32 v[114:115], v[114:115], v[2:3] op_sel:[0,1] op_sel_hi:[1,1]
	v_add_f32_dpp v116, v116, v116 quad_perm:[1,0,3,2] row_mask:0xf bank_mask:0xf bound_ctrl:1
	v_pk_fma_f32 v[112:113], v[4:5], v[104:105], v[112:113]
	v_pk_fma_f32 v[114:115], v[6:7], v[106:107], v[114:115]
	v_add_f32_dpp v116, v116, v116 quad_perm:[2,3,0,1] row_mask:0xf bank_mask:0xf bound_ctrl:1
	v_pk_mul_f32 v[72:73], v[72:73], v[4:5]
	v_pk_fma_f32 v[72:73], v[6:7], v[74:75], v[72:73]
	v_add_f32_dpp v116, v116, v116 row_half_mirror row_mask:0xf bank_mask:0xf bound_ctrl:1
	v_add_f32_e32 v8, v72, v73
	ds_read_b128 v[76:79], v10 offset:22016
	ds_read2st64_b32 v[2:3], v11 offset0:89 offset1:95
	ds_read_b128 v[80:83], v10 offset:22272
	ds_read_b128 v[68:71], v10 offset:21504
	ds_read_b128 v[84:87], v10 offset:22528
	ds_read_b128 v[72:75], v10 offset:21760
	ds_write2st64_b32 v12, v9, v8 offset0:24 offset1:26
	v_add_f32_dpp v116, v116, v116 row_mirror row_mask:0xf bank_mask:0xf bound_ctrl:1
	v_pk_fma_f32 v[4:5], v[116:117], v[120:121], v[112:113] op_sel_hi:[0,1,1]
	v_pk_fma_f32 v[6:7], v[116:117], v[122:123], v[114:115] op_sel_hi:[0,1,1]
	s_waitcnt lgkmcnt(13)
	v_pk_mul_f32 v[40:41], v[4:5], v[40:41]
	v_pk_fma_f32 v[40:41], v[6:7], v[42:43], v[40:41]
	v_add_f32_e32 v40, v40, v41
	v_pk_mul_f32 v[36:37], v[36:37], v[0:1] op_sel_hi:[1,0]
	v_pk_mul_f32 v[38:39], v[38:39], v[0:1] op_sel_hi:[1,0]
	v_add_f32_dpp v40, v40, v40 quad_perm:[1,0,3,2] row_mask:0xf bank_mask:0xf bound_ctrl:1
	v_pk_fma_f32 v[36:37], v[4:5], v[28:29], v[36:37]
	v_pk_fma_f32 v[38:39], v[6:7], v[30:31], v[38:39]
	v_add_f32_dpp v40, v40, v40 quad_perm:[2,3,0,1] row_mask:0xf bank_mask:0xf bound_ctrl:1
	v_pk_mul_f32 v[108:109], v[108:109], v[4:5]
	v_pk_fma_f32 v[108:109], v[6:7], v[110:111], v[108:109]
	v_add_f32_dpp v40, v40, v40 row_half_mirror row_mask:0xf bank_mask:0xf bound_ctrl:1
	v_add_f32_e32 v9, v108, v109
	ds_read_b128 v[112:115], v10 offset:23552
	ds_read_b128 v[116:119], v10 offset:23808
	ds_read_b128 v[104:107], v10 offset:23040
	ds_read_b128 v[120:123], v10 offset:24064
	ds_read_b128 v[108:111], v10 offset:23296
	v_add_f32_dpp v40, v40, v40 row_mirror row_mask:0xf bank_mask:0xf bound_ctrl:1
	v_pk_fma_f32 v[4:5], v[40:41], v[44:45], v[36:37] op_sel_hi:[0,1,1]
	v_pk_fma_f32 v[6:7], v[40:41], v[46:47], v[38:39] op_sel_hi:[0,1,1]
	s_waitcnt lgkmcnt(12)
	v_pk_mul_f32 v[60:61], v[4:5], v[60:61]
	v_pk_fma_f32 v[60:61], v[6:7], v[62:63], v[60:61]
	v_add_f32_e32 v60, v60, v61
	v_pk_mul_f32 v[56:57], v[56:57], v[0:1] op_sel:[0,1] op_sel_hi:[1,1]
	v_pk_mul_f32 v[58:59], v[58:59], v[0:1] op_sel:[0,1] op_sel_hi:[1,1]
	v_add_f32_dpp v60, v60, v60 quad_perm:[1,0,3,2] row_mask:0xf bank_mask:0xf bound_ctrl:1
	v_pk_fma_f32 v[56:57], v[4:5], v[48:49], v[56:57]
	v_pk_fma_f32 v[58:59], v[6:7], v[50:51], v[58:59]
	v_add_f32_dpp v60, v60, v60 quad_perm:[2,3,0,1] row_mask:0xf bank_mask:0xf bound_ctrl:1
	v_pk_mul_f32 v[32:33], v[32:33], v[4:5]
	v_pk_fma_f32 v[32:33], v[6:7], v[34:35], v[32:33]
	v_add_f32_dpp v60, v60, v60 row_half_mirror row_mask:0xf bank_mask:0xf bound_ctrl:1
	v_add_f32_e32 v8, v32, v33
	ds_read_b128 v[36:39], v10 offset:25088
	ds_read2st64_b32 v[0:1], v11 offset0:101 offset1:107
	ds_read_b128 v[40:43], v10 offset:25344
	ds_read_b128 v[28:31], v10 offset:24576
	ds_read_b128 v[44:47], v10 offset:25600
	ds_read_b128 v[32:35], v10 offset:24832
	ds_write2st64_b32 v12, v9, v8 offset0:28 offset1:30
	v_add_f32_dpp v60, v60, v60 row_mirror row_mask:0xf bank_mask:0xf bound_ctrl:1
	v_pk_fma_f32 v[4:5], v[60:61], v[64:65], v[56:57] op_sel_hi:[0,1,1]
	v_pk_fma_f32 v[6:7], v[60:61], v[66:67], v[58:59] op_sel_hi:[0,1,1]
	s_waitcnt lgkmcnt(13)
	v_pk_mul_f32 v[80:81], v[4:5], v[80:81]
	v_pk_fma_f32 v[80:81], v[6:7], v[82:83], v[80:81]
	v_add_f32_e32 v80, v80, v81
	v_pk_mul_f32 v[76:77], v[76:77], v[2:3] op_sel_hi:[1,0]
	v_pk_mul_f32 v[78:79], v[78:79], v[2:3] op_sel_hi:[1,0]
	v_add_f32_dpp v80, v80, v80 quad_perm:[1,0,3,2] row_mask:0xf bank_mask:0xf bound_ctrl:1
	v_pk_fma_f32 v[76:77], v[4:5], v[68:69], v[76:77]
	v_pk_fma_f32 v[78:79], v[6:7], v[70:71], v[78:79]
	v_add_f32_dpp v80, v80, v80 quad_perm:[2,3,0,1] row_mask:0xf bank_mask:0xf bound_ctrl:1
	v_pk_mul_f32 v[52:53], v[52:53], v[4:5]
	v_pk_fma_f32 v[52:53], v[6:7], v[54:55], v[52:53]
	v_add_f32_dpp v80, v80, v80 row_half_mirror row_mask:0xf bank_mask:0xf bound_ctrl:1
	v_add_f32_e32 v9, v52, v53
	ds_read_b128 v[56:59], v10 offset:26624
	ds_read_b128 v[60:63], v10 offset:26880
	ds_read_b128 v[48:51], v10 offset:26112
	ds_read_b128 v[64:67], v10 offset:27136
	ds_read_b128 v[52:55], v10 offset:26368
	v_add_f32_dpp v80, v80, v80 row_mirror row_mask:0xf bank_mask:0xf bound_ctrl:1
	v_pk_fma_f32 v[4:5], v[80:81], v[84:85], v[76:77] op_sel_hi:[0,1,1]
	v_pk_fma_f32 v[6:7], v[80:81], v[86:87], v[78:79] op_sel_hi:[0,1,1]
	s_waitcnt lgkmcnt(12)
	v_pk_mul_f32 v[116:117], v[4:5], v[116:117]
	v_pk_fma_f32 v[116:117], v[6:7], v[118:119], v[116:117]
	v_add_f32_e32 v116, v116, v117
	v_pk_mul_f32 v[112:113], v[112:113], v[2:3] op_sel:[0,1] op_sel_hi:[1,1]
	v_pk_mul_f32 v[114:115], v[114:115], v[2:3] op_sel:[0,1] op_sel_hi:[1,1]
	v_add_f32_dpp v116, v116, v116 quad_perm:[1,0,3,2] row_mask:0xf bank_mask:0xf bound_ctrl:1
	v_pk_fma_f32 v[112:113], v[4:5], v[104:105], v[112:113]
	v_pk_fma_f32 v[114:115], v[6:7], v[106:107], v[114:115]
	v_add_f32_dpp v116, v116, v116 quad_perm:[2,3,0,1] row_mask:0xf bank_mask:0xf bound_ctrl:1
	v_pk_mul_f32 v[72:73], v[72:73], v[4:5]
	v_pk_fma_f32 v[72:73], v[6:7], v[74:75], v[72:73]
	v_add_f32_dpp v116, v116, v116 row_half_mirror row_mask:0xf bank_mask:0xf bound_ctrl:1
	v_add_f32_e32 v8, v72, v73
	ds_read_b128 v[76:79], v10 offset:28160
	ds_read2st64_b32 v[2:3], v11 offset0:113 offset1:119
	ds_read_b128 v[80:83], v10 offset:28416
	ds_read_b128 v[68:71], v10 offset:27648
	ds_read_b128 v[84:87], v10 offset:28672
	ds_read_b128 v[72:75], v10 offset:27904
	ds_write2st64_b32 v12, v9, v8 offset0:32 offset1:34
	v_add_f32_dpp v116, v116, v116 row_mirror row_mask:0xf bank_mask:0xf bound_ctrl:1
	v_pk_fma_f32 v[4:5], v[116:117], v[120:121], v[112:113] op_sel_hi:[0,1,1]
	v_pk_fma_f32 v[6:7], v[116:117], v[122:123], v[114:115] op_sel_hi:[0,1,1]
	s_waitcnt lgkmcnt(13)
	v_pk_mul_f32 v[40:41], v[4:5], v[40:41]
	v_pk_fma_f32 v[40:41], v[6:7], v[42:43], v[40:41]
	v_add_f32_e32 v40, v40, v41
	v_pk_mul_f32 v[36:37], v[36:37], v[0:1] op_sel_hi:[1,0]
	v_pk_mul_f32 v[38:39], v[38:39], v[0:1] op_sel_hi:[1,0]
	v_add_f32_dpp v40, v40, v40 quad_perm:[1,0,3,2] row_mask:0xf bank_mask:0xf bound_ctrl:1
	v_pk_fma_f32 v[36:37], v[4:5], v[28:29], v[36:37]
	v_pk_fma_f32 v[38:39], v[6:7], v[30:31], v[38:39]
	v_add_f32_dpp v40, v40, v40 quad_perm:[2,3,0,1] row_mask:0xf bank_mask:0xf bound_ctrl:1
	v_pk_mul_f32 v[108:109], v[108:109], v[4:5]
	v_pk_fma_f32 v[108:109], v[6:7], v[110:111], v[108:109]
	v_add_f32_dpp v40, v40, v40 row_half_mirror row_mask:0xf bank_mask:0xf bound_ctrl:1
	v_add_f32_e32 v9, v108, v109
	ds_read_b128 v[112:115], v10 offset:29696
	ds_read_b128 v[116:119], v10 offset:29952
	ds_read_b128 v[104:107], v10 offset:29184
	ds_read_b128 v[120:123], v10 offset:30208
	ds_read_b128 v[108:111], v10 offset:29440
	v_add_f32_dpp v40, v40, v40 row_mirror row_mask:0xf bank_mask:0xf bound_ctrl:1
	v_pk_fma_f32 v[4:5], v[40:41], v[44:45], v[36:37] op_sel_hi:[0,1,1]
	v_pk_fma_f32 v[6:7], v[40:41], v[46:47], v[38:39] op_sel_hi:[0,1,1]
	s_waitcnt lgkmcnt(12)
	v_pk_mul_f32 v[60:61], v[4:5], v[60:61]
	v_pk_fma_f32 v[60:61], v[6:7], v[62:63], v[60:61]
	v_add_f32_e32 v60, v60, v61
	v_pk_mul_f32 v[56:57], v[56:57], v[0:1] op_sel:[0,1] op_sel_hi:[1,1]
	v_pk_mul_f32 v[58:59], v[58:59], v[0:1] op_sel:[0,1] op_sel_hi:[1,1]
	v_add_f32_dpp v60, v60, v60 quad_perm:[1,0,3,2] row_mask:0xf bank_mask:0xf bound_ctrl:1
	v_pk_fma_f32 v[56:57], v[4:5], v[48:49], v[56:57]
	v_pk_fma_f32 v[58:59], v[6:7], v[50:51], v[58:59]
	v_add_f32_dpp v60, v60, v60 quad_perm:[2,3,0,1] row_mask:0xf bank_mask:0xf bound_ctrl:1
	v_pk_mul_f32 v[32:33], v[32:33], v[4:5]
	v_pk_fma_f32 v[32:33], v[6:7], v[34:35], v[32:33]
	v_add_f32_dpp v60, v60, v60 row_half_mirror row_mask:0xf bank_mask:0xf bound_ctrl:1
	v_add_f32_e32 v8, v32, v33
	ds_read_b128 v[36:39], v10 offset:31232
	ds_read2st64_b32 v[0:1], v11 offset0:125 offset1:131
	ds_read_b128 v[40:43], v10 offset:31488
	ds_read_b128 v[28:31], v10 offset:30720
	ds_read_b128 v[44:47], v10 offset:31744
	ds_read_b128 v[32:35], v10 offset:30976
	ds_write2st64_b32 v12, v9, v8 offset0:36 offset1:38
	v_add_f32_dpp v60, v60, v60 row_mirror row_mask:0xf bank_mask:0xf bound_ctrl:1
	v_pk_fma_f32 v[4:5], v[60:61], v[64:65], v[56:57] op_sel_hi:[0,1,1]
	v_pk_fma_f32 v[6:7], v[60:61], v[66:67], v[58:59] op_sel_hi:[0,1,1]
	s_waitcnt lgkmcnt(13)
	v_pk_mul_f32 v[80:81], v[4:5], v[80:81]
	v_pk_fma_f32 v[80:81], v[6:7], v[82:83], v[80:81]
	v_add_f32_e32 v80, v80, v81
	v_pk_mul_f32 v[76:77], v[76:77], v[2:3] op_sel_hi:[1,0]
	v_pk_mul_f32 v[78:79], v[78:79], v[2:3] op_sel_hi:[1,0]
	v_add_f32_dpp v80, v80, v80 quad_perm:[1,0,3,2] row_mask:0xf bank_mask:0xf bound_ctrl:1
	v_pk_fma_f32 v[76:77], v[4:5], v[68:69], v[76:77]
	v_pk_fma_f32 v[78:79], v[6:7], v[70:71], v[78:79]
	v_add_f32_dpp v80, v80, v80 quad_perm:[2,3,0,1] row_mask:0xf bank_mask:0xf bound_ctrl:1
	v_pk_mul_f32 v[52:53], v[52:53], v[4:5]
	v_pk_fma_f32 v[52:53], v[6:7], v[54:55], v[52:53]
	v_add_f32_dpp v80, v80, v80 row_half_mirror row_mask:0xf bank_mask:0xf bound_ctrl:1
	v_add_f32_e32 v9, v52, v53
	ds_read_b128 v[56:59], v10 offset:32768
	ds_read_b128 v[60:63], v10 offset:33024
	ds_read_b128 v[48:51], v10 offset:32256
	ds_read_b128 v[64:67], v10 offset:33280
	ds_read_b128 v[52:55], v10 offset:32512
	v_add_f32_dpp v80, v80, v80 row_mirror row_mask:0xf bank_mask:0xf bound_ctrl:1
	v_pk_fma_f32 v[4:5], v[80:81], v[84:85], v[76:77] op_sel_hi:[0,1,1]
	v_pk_fma_f32 v[6:7], v[80:81], v[86:87], v[78:79] op_sel_hi:[0,1,1]
	s_waitcnt lgkmcnt(12)
	v_pk_mul_f32 v[116:117], v[4:5], v[116:117]
	v_pk_fma_f32 v[116:117], v[6:7], v[118:119], v[116:117]
	v_add_f32_e32 v116, v116, v117
	v_pk_mul_f32 v[112:113], v[112:113], v[2:3] op_sel:[0,1] op_sel_hi:[1,1]
	v_pk_mul_f32 v[114:115], v[114:115], v[2:3] op_sel:[0,1] op_sel_hi:[1,1]
	v_add_f32_dpp v116, v116, v116 quad_perm:[1,0,3,2] row_mask:0xf bank_mask:0xf bound_ctrl:1
	v_pk_fma_f32 v[112:113], v[4:5], v[104:105], v[112:113]
	v_pk_fma_f32 v[114:115], v[6:7], v[106:107], v[114:115]
	v_add_f32_dpp v116, v116, v116 quad_perm:[2,3,0,1] row_mask:0xf bank_mask:0xf bound_ctrl:1
	v_pk_mul_f32 v[72:73], v[72:73], v[4:5]
	v_pk_fma_f32 v[72:73], v[6:7], v[74:75], v[72:73]
	v_add_f32_dpp v116, v116, v116 row_half_mirror row_mask:0xf bank_mask:0xf bound_ctrl:1
	v_add_f32_e32 v8, v72, v73
	ds_read_b128 v[76:79], v10 offset:34304
	ds_read2st64_b32 v[2:3], v11 offset0:137 offset1:143
	ds_read_b128 v[80:83], v10 offset:34560
	ds_read_b128 v[68:71], v10 offset:33792
	ds_read_b128 v[84:87], v10 offset:34816
	ds_read_b128 v[72:75], v10 offset:34048
	ds_write2st64_b32 v12, v9, v8 offset0:40 offset1:42
	v_add_f32_dpp v116, v116, v116 row_mirror row_mask:0xf bank_mask:0xf bound_ctrl:1
	v_pk_fma_f32 v[4:5], v[116:117], v[120:121], v[112:113] op_sel_hi:[0,1,1]
	v_pk_fma_f32 v[6:7], v[116:117], v[122:123], v[114:115] op_sel_hi:[0,1,1]
	s_waitcnt lgkmcnt(13)
	v_pk_mul_f32 v[40:41], v[4:5], v[40:41]
	v_pk_fma_f32 v[40:41], v[6:7], v[42:43], v[40:41]
	v_add_f32_e32 v40, v40, v41
	v_pk_mul_f32 v[36:37], v[36:37], v[0:1] op_sel_hi:[1,0]
	v_pk_mul_f32 v[38:39], v[38:39], v[0:1] op_sel_hi:[1,0]
	v_add_f32_dpp v40, v40, v40 quad_perm:[1,0,3,2] row_mask:0xf bank_mask:0xf bound_ctrl:1
	v_pk_fma_f32 v[36:37], v[4:5], v[28:29], v[36:37]
	v_pk_fma_f32 v[38:39], v[6:7], v[30:31], v[38:39]
	v_add_f32_dpp v40, v40, v40 quad_perm:[2,3,0,1] row_mask:0xf bank_mask:0xf bound_ctrl:1
	v_pk_mul_f32 v[108:109], v[108:109], v[4:5]
	v_pk_fma_f32 v[108:109], v[6:7], v[110:111], v[108:109]
	v_add_f32_dpp v40, v40, v40 row_half_mirror row_mask:0xf bank_mask:0xf bound_ctrl:1
	v_add_f32_e32 v9, v108, v109
	ds_read_b128 v[112:115], v10 offset:35840
	ds_read_b128 v[116:119], v10 offset:36096
	ds_read_b128 v[104:107], v10 offset:35328
	ds_read_b128 v[120:123], v10 offset:36352
	ds_read_b128 v[108:111], v10 offset:35584
	v_add_f32_dpp v40, v40, v40 row_mirror row_mask:0xf bank_mask:0xf bound_ctrl:1
	v_pk_fma_f32 v[4:5], v[40:41], v[44:45], v[36:37] op_sel_hi:[0,1,1]
	v_pk_fma_f32 v[6:7], v[40:41], v[46:47], v[38:39] op_sel_hi:[0,1,1]
	s_waitcnt lgkmcnt(12)
	v_pk_mul_f32 v[60:61], v[4:5], v[60:61]
	v_pk_fma_f32 v[60:61], v[6:7], v[62:63], v[60:61]
	v_add_f32_e32 v60, v60, v61
	v_pk_mul_f32 v[56:57], v[56:57], v[0:1] op_sel:[0,1] op_sel_hi:[1,1]
	v_pk_mul_f32 v[58:59], v[58:59], v[0:1] op_sel:[0,1] op_sel_hi:[1,1]
	v_add_f32_dpp v60, v60, v60 quad_perm:[1,0,3,2] row_mask:0xf bank_mask:0xf bound_ctrl:1
	v_pk_fma_f32 v[56:57], v[4:5], v[48:49], v[56:57]
	v_pk_fma_f32 v[58:59], v[6:7], v[50:51], v[58:59]
	v_add_f32_dpp v60, v60, v60 quad_perm:[2,3,0,1] row_mask:0xf bank_mask:0xf bound_ctrl:1
	v_pk_mul_f32 v[32:33], v[32:33], v[4:5]
	v_pk_fma_f32 v[32:33], v[6:7], v[34:35], v[32:33]
	v_add_f32_dpp v60, v60, v60 row_half_mirror row_mask:0xf bank_mask:0xf bound_ctrl:1
	v_add_f32_e32 v8, v32, v33
	ds_read_b128 v[36:39], v10 offset:37376
	ds_read2st64_b32 v[0:1], v11 offset0:149 offset1:155
	ds_read_b128 v[40:43], v10 offset:37632
	ds_read_b128 v[28:31], v10 offset:36864
	ds_read_b128 v[44:47], v10 offset:37888
	ds_read_b128 v[32:35], v10 offset:37120
	ds_write2st64_b32 v12, v9, v8 offset0:44 offset1:46
	v_add_f32_dpp v60, v60, v60 row_mirror row_mask:0xf bank_mask:0xf bound_ctrl:1
	v_pk_fma_f32 v[4:5], v[60:61], v[64:65], v[56:57] op_sel_hi:[0,1,1]
	v_pk_fma_f32 v[6:7], v[60:61], v[66:67], v[58:59] op_sel_hi:[0,1,1]
	s_waitcnt lgkmcnt(13)
	v_pk_mul_f32 v[80:81], v[4:5], v[80:81]
	v_pk_fma_f32 v[80:81], v[6:7], v[82:83], v[80:81]
	v_add_f32_e32 v80, v80, v81
	v_pk_mul_f32 v[76:77], v[76:77], v[2:3] op_sel_hi:[1,0]
	v_pk_mul_f32 v[78:79], v[78:79], v[2:3] op_sel_hi:[1,0]
	v_add_f32_dpp v80, v80, v80 quad_perm:[1,0,3,2] row_mask:0xf bank_mask:0xf bound_ctrl:1
	v_pk_fma_f32 v[76:77], v[4:5], v[68:69], v[76:77]
	v_pk_fma_f32 v[78:79], v[6:7], v[70:71], v[78:79]
	v_add_f32_dpp v80, v80, v80 quad_perm:[2,3,0,1] row_mask:0xf bank_mask:0xf bound_ctrl:1
	v_pk_mul_f32 v[52:53], v[52:53], v[4:5]
	v_pk_fma_f32 v[52:53], v[6:7], v[54:55], v[52:53]
	v_add_f32_dpp v80, v80, v80 row_half_mirror row_mask:0xf bank_mask:0xf bound_ctrl:1
	v_add_f32_e32 v9, v52, v53
	ds_read_b128 v[56:59], v10 offset:38912
	ds_read_b128 v[60:63], v10 offset:39168
	ds_read_b128 v[48:51], v10 offset:38400
	ds_read_b128 v[64:67], v10 offset:39424
	ds_read_b128 v[52:55], v10 offset:38656
	v_add_f32_dpp v80, v80, v80 row_mirror row_mask:0xf bank_mask:0xf bound_ctrl:1
	v_pk_fma_f32 v[4:5], v[80:81], v[84:85], v[76:77] op_sel_hi:[0,1,1]
	v_pk_fma_f32 v[6:7], v[80:81], v[86:87], v[78:79] op_sel_hi:[0,1,1]
	s_waitcnt lgkmcnt(12)
	v_pk_mul_f32 v[116:117], v[4:5], v[116:117]
	v_pk_fma_f32 v[116:117], v[6:7], v[118:119], v[116:117]
	v_add_f32_e32 v116, v116, v117
	v_pk_mul_f32 v[112:113], v[112:113], v[2:3] op_sel:[0,1] op_sel_hi:[1,1]
	v_pk_mul_f32 v[114:115], v[114:115], v[2:3] op_sel:[0,1] op_sel_hi:[1,1]
	v_add_f32_dpp v116, v116, v116 quad_perm:[1,0,3,2] row_mask:0xf bank_mask:0xf bound_ctrl:1
	v_pk_fma_f32 v[112:113], v[4:5], v[104:105], v[112:113]
	v_pk_fma_f32 v[114:115], v[6:7], v[106:107], v[114:115]
	v_add_f32_dpp v116, v116, v116 quad_perm:[2,3,0,1] row_mask:0xf bank_mask:0xf bound_ctrl:1
	v_pk_mul_f32 v[72:73], v[72:73], v[4:5]
	v_pk_fma_f32 v[72:73], v[6:7], v[74:75], v[72:73]
	v_add_f32_dpp v116, v116, v116 row_half_mirror row_mask:0xf bank_mask:0xf bound_ctrl:1
	v_add_f32_e32 v8, v72, v73
	ds_read_b128 v[76:79], v10 offset:40448
	ds_read2st64_b32 v[2:3], v11 offset0:161 offset1:167
	ds_read_b128 v[80:83], v10 offset:40704
	ds_read_b128 v[68:71], v10 offset:39936
	ds_read_b128 v[84:87], v10 offset:40960
	ds_read_b128 v[72:75], v10 offset:40192
	ds_write2st64_b32 v12, v9, v8 offset0:48 offset1:50
	v_add_f32_dpp v116, v116, v116 row_mirror row_mask:0xf bank_mask:0xf bound_ctrl:1
	v_pk_fma_f32 v[4:5], v[116:117], v[120:121], v[112:113] op_sel_hi:[0,1,1]
	v_pk_fma_f32 v[6:7], v[116:117], v[122:123], v[114:115] op_sel_hi:[0,1,1]
	s_waitcnt lgkmcnt(13)
	v_pk_mul_f32 v[40:41], v[4:5], v[40:41]
	v_pk_fma_f32 v[40:41], v[6:7], v[42:43], v[40:41]
	v_add_f32_e32 v40, v40, v41
	v_pk_mul_f32 v[36:37], v[36:37], v[0:1] op_sel_hi:[1,0]
	v_pk_mul_f32 v[38:39], v[38:39], v[0:1] op_sel_hi:[1,0]
	v_add_f32_dpp v40, v40, v40 quad_perm:[1,0,3,2] row_mask:0xf bank_mask:0xf bound_ctrl:1
	v_pk_fma_f32 v[36:37], v[4:5], v[28:29], v[36:37]
	v_pk_fma_f32 v[38:39], v[6:7], v[30:31], v[38:39]
	v_add_f32_dpp v40, v40, v40 quad_perm:[2,3,0,1] row_mask:0xf bank_mask:0xf bound_ctrl:1
	v_pk_mul_f32 v[108:109], v[108:109], v[4:5]
	v_pk_fma_f32 v[108:109], v[6:7], v[110:111], v[108:109]
	v_add_f32_dpp v40, v40, v40 row_half_mirror row_mask:0xf bank_mask:0xf bound_ctrl:1
	v_add_f32_e32 v9, v108, v109
	ds_read_b128 v[112:115], v10 offset:41984
	ds_read_b128 v[116:119], v10 offset:42240
	ds_read_b128 v[104:107], v10 offset:41472
	ds_read_b128 v[120:123], v10 offset:42496
	ds_read_b128 v[108:111], v10 offset:41728
	v_add_f32_dpp v40, v40, v40 row_mirror row_mask:0xf bank_mask:0xf bound_ctrl:1
	v_pk_fma_f32 v[4:5], v[40:41], v[44:45], v[36:37] op_sel_hi:[0,1,1]
	v_pk_fma_f32 v[6:7], v[40:41], v[46:47], v[38:39] op_sel_hi:[0,1,1]
	s_waitcnt lgkmcnt(12)
	v_pk_mul_f32 v[60:61], v[4:5], v[60:61]
	v_pk_fma_f32 v[60:61], v[6:7], v[62:63], v[60:61]
	v_add_f32_e32 v60, v60, v61
	v_pk_mul_f32 v[56:57], v[56:57], v[0:1] op_sel:[0,1] op_sel_hi:[1,1]
	v_pk_mul_f32 v[58:59], v[58:59], v[0:1] op_sel:[0,1] op_sel_hi:[1,1]
	v_add_f32_dpp v60, v60, v60 quad_perm:[1,0,3,2] row_mask:0xf bank_mask:0xf bound_ctrl:1
	v_pk_fma_f32 v[56:57], v[4:5], v[48:49], v[56:57]
	v_pk_fma_f32 v[58:59], v[6:7], v[50:51], v[58:59]
	v_add_f32_dpp v60, v60, v60 quad_perm:[2,3,0,1] row_mask:0xf bank_mask:0xf bound_ctrl:1
	v_pk_mul_f32 v[32:33], v[32:33], v[4:5]
	v_pk_fma_f32 v[32:33], v[6:7], v[34:35], v[32:33]
	v_add_f32_dpp v60, v60, v60 row_half_mirror row_mask:0xf bank_mask:0xf bound_ctrl:1
	v_add_f32_e32 v8, v32, v33
	ds_read_b128 v[36:39], v10 offset:43520
	ds_read2st64_b32 v[0:1], v11 offset0:173 offset1:179
	ds_read_b128 v[40:43], v10 offset:43776
	ds_read_b128 v[28:31], v10 offset:43008
	ds_read_b128 v[44:47], v10 offset:44032
	ds_read_b128 v[32:35], v10 offset:43264
	ds_write2st64_b32 v12, v9, v8 offset0:52 offset1:54
	v_add_f32_dpp v60, v60, v60 row_mirror row_mask:0xf bank_mask:0xf bound_ctrl:1
	v_pk_fma_f32 v[4:5], v[60:61], v[64:65], v[56:57] op_sel_hi:[0,1,1]
	v_pk_fma_f32 v[6:7], v[60:61], v[66:67], v[58:59] op_sel_hi:[0,1,1]
	s_waitcnt lgkmcnt(13)
	v_pk_mul_f32 v[80:81], v[4:5], v[80:81]
	v_pk_fma_f32 v[80:81], v[6:7], v[82:83], v[80:81]
	v_add_f32_e32 v80, v80, v81
	v_pk_mul_f32 v[76:77], v[76:77], v[2:3] op_sel_hi:[1,0]
	v_pk_mul_f32 v[78:79], v[78:79], v[2:3] op_sel_hi:[1,0]
	v_add_f32_dpp v80, v80, v80 quad_perm:[1,0,3,2] row_mask:0xf bank_mask:0xf bound_ctrl:1
	v_pk_fma_f32 v[76:77], v[4:5], v[68:69], v[76:77]
	v_pk_fma_f32 v[78:79], v[6:7], v[70:71], v[78:79]
	v_add_f32_dpp v80, v80, v80 quad_perm:[2,3,0,1] row_mask:0xf bank_mask:0xf bound_ctrl:1
	v_pk_mul_f32 v[52:53], v[52:53], v[4:5]
	v_pk_fma_f32 v[52:53], v[6:7], v[54:55], v[52:53]
	v_add_f32_dpp v80, v80, v80 row_half_mirror row_mask:0xf bank_mask:0xf bound_ctrl:1
	v_add_f32_e32 v9, v52, v53
	ds_read_b128 v[56:59], v10 offset:45056
	ds_read_b128 v[60:63], v10 offset:45312
	ds_read_b128 v[48:51], v10 offset:44544
	ds_read_b128 v[64:67], v10 offset:45568
	ds_read_b128 v[52:55], v10 offset:44800
	v_add_f32_dpp v80, v80, v80 row_mirror row_mask:0xf bank_mask:0xf bound_ctrl:1
	v_pk_fma_f32 v[4:5], v[80:81], v[84:85], v[76:77] op_sel_hi:[0,1,1]
	v_pk_fma_f32 v[6:7], v[80:81], v[86:87], v[78:79] op_sel_hi:[0,1,1]
	s_waitcnt lgkmcnt(12)
	v_pk_mul_f32 v[116:117], v[4:5], v[116:117]
	v_pk_fma_f32 v[116:117], v[6:7], v[118:119], v[116:117]
	v_add_f32_e32 v116, v116, v117
	v_pk_mul_f32 v[112:113], v[112:113], v[2:3] op_sel:[0,1] op_sel_hi:[1,1]
	v_pk_mul_f32 v[114:115], v[114:115], v[2:3] op_sel:[0,1] op_sel_hi:[1,1]
	v_add_f32_dpp v116, v116, v116 quad_perm:[1,0,3,2] row_mask:0xf bank_mask:0xf bound_ctrl:1
	v_pk_fma_f32 v[112:113], v[4:5], v[104:105], v[112:113]
	v_pk_fma_f32 v[114:115], v[6:7], v[106:107], v[114:115]
	v_add_f32_dpp v116, v116, v116 quad_perm:[2,3,0,1] row_mask:0xf bank_mask:0xf bound_ctrl:1
	v_pk_mul_f32 v[72:73], v[72:73], v[4:5]
	v_pk_fma_f32 v[72:73], v[6:7], v[74:75], v[72:73]
	v_add_f32_dpp v116, v116, v116 row_half_mirror row_mask:0xf bank_mask:0xf bound_ctrl:1
	v_add_f32_e32 v8, v72, v73
	ds_read_b128 v[76:79], v10 offset:46592
	ds_read2st64_b32 v[2:3], v11 offset0:185 offset1:191
	ds_read_b128 v[80:83], v10 offset:46848
	ds_read_b128 v[68:71], v10 offset:46080
	ds_read_b128 v[84:87], v10 offset:47104
	ds_read_b128 v[72:75], v10 offset:46336
	ds_write2st64_b32 v12, v9, v8 offset0:56 offset1:58
	v_add_f32_dpp v116, v116, v116 row_mirror row_mask:0xf bank_mask:0xf bound_ctrl:1
	v_pk_fma_f32 v[4:5], v[116:117], v[120:121], v[112:113] op_sel_hi:[0,1,1]
	v_pk_fma_f32 v[6:7], v[116:117], v[122:123], v[114:115] op_sel_hi:[0,1,1]
	s_waitcnt lgkmcnt(13)
	v_pk_mul_f32 v[40:41], v[4:5], v[40:41]
	v_pk_fma_f32 v[40:41], v[6:7], v[42:43], v[40:41]
	v_add_f32_e32 v40, v40, v41
	v_pk_mul_f32 v[36:37], v[36:37], v[0:1] op_sel_hi:[1,0]
	v_pk_mul_f32 v[38:39], v[38:39], v[0:1] op_sel_hi:[1,0]
	v_add_f32_dpp v40, v40, v40 quad_perm:[1,0,3,2] row_mask:0xf bank_mask:0xf bound_ctrl:1
	v_pk_fma_f32 v[36:37], v[4:5], v[28:29], v[36:37]
	v_pk_fma_f32 v[38:39], v[6:7], v[30:31], v[38:39]
	v_add_f32_dpp v40, v40, v40 quad_perm:[2,3,0,1] row_mask:0xf bank_mask:0xf bound_ctrl:1
	v_pk_mul_f32 v[108:109], v[108:109], v[4:5]
	v_pk_fma_f32 v[108:109], v[6:7], v[110:111], v[108:109]
	v_add_f32_dpp v40, v40, v40 row_half_mirror row_mask:0xf bank_mask:0xf bound_ctrl:1
	v_add_f32_e32 v9, v108, v109
	ds_read_b128 v[112:115], v10 offset:48128
	ds_read_b128 v[116:119], v10 offset:48384
	ds_read_b128 v[104:107], v10 offset:47616
	ds_read_b128 v[120:123], v10 offset:48640
	ds_read_b128 v[108:111], v10 offset:47872
	v_add_f32_dpp v40, v40, v40 row_mirror row_mask:0xf bank_mask:0xf bound_ctrl:1
	v_pk_fma_f32 v[4:5], v[40:41], v[44:45], v[36:37] op_sel_hi:[0,1,1]
	v_pk_fma_f32 v[6:7], v[40:41], v[46:47], v[38:39] op_sel_hi:[0,1,1]
	s_waitcnt lgkmcnt(12)
	v_pk_mul_f32 v[60:61], v[4:5], v[60:61]
	v_pk_fma_f32 v[60:61], v[6:7], v[62:63], v[60:61]
	v_add_f32_e32 v60, v60, v61
	v_pk_mul_f32 v[56:57], v[56:57], v[0:1] op_sel:[0,1] op_sel_hi:[1,1]
	v_pk_mul_f32 v[58:59], v[58:59], v[0:1] op_sel:[0,1] op_sel_hi:[1,1]
	v_add_f32_dpp v60, v60, v60 quad_perm:[1,0,3,2] row_mask:0xf bank_mask:0xf bound_ctrl:1
	v_pk_fma_f32 v[56:57], v[4:5], v[48:49], v[56:57]
	v_pk_fma_f32 v[58:59], v[6:7], v[50:51], v[58:59]
	v_add_f32_dpp v60, v60, v60 quad_perm:[2,3,0,1] row_mask:0xf bank_mask:0xf bound_ctrl:1
	v_pk_mul_f32 v[32:33], v[32:33], v[4:5]
	v_pk_fma_f32 v[32:33], v[6:7], v[34:35], v[32:33]
	v_add_f32_dpp v60, v60, v60 row_half_mirror row_mask:0xf bank_mask:0xf bound_ctrl:1
	v_add_f32_e32 v8, v32, v33
	ds_write2st64_b32 v12, v9, v8 offset0:60 offset1:62
	s_nop 0
	v_add_f32_dpp v60, v60, v60 row_mirror row_mask:0xf bank_mask:0xf bound_ctrl:1
